# FOX: forget-gate decay folded into the QK MFMA accumulator init (C operand) instead of 16 packed adds per tile
# speedup vs baseline: 1.0272x; 1.0056x over previous
;     ...
;         if (active) {
;             f32x16 sc[2];
; #pragma unroll
;             for (int i = 0; i < 16; ++i) { sc[0][i] = 0.f; sc[1][i] = 0.f; }
; #pragma unroll
;             for (int s = 0; s < NKS; ++s) {
;                 const bf16x8 k0 = *(const bf16x8*)(sK + r * KS + 16 * s + 8 * h), k1 = *(const bf16x8*)(sK + (32 + r) * KS + 16 * s + 8 * h);
;                 sc[0] = MFMA32(k0, qf[s], sc[0]);
;                 sc[1] = MFMA32(k1, qf[s], sc[1]);
;             }
;             bf16x8 pf[4];
;             if (MODE == 1) {
;                 float u[2][16];
; #pragma unroll
;                 for (int mt = 0; mt < 2; ++mt)
; #pragma unroll
;                     for (int i = 0; i < 16; ++i) sc[mt][i] = __builtin_amdgcn_rcpf(1.f + fexp2(-sc[mt][i]));
;                 if (64 * kt + 63 >= q0 + 32 * w) {
; #pragma unroll
;                     for (int mt = 0; mt < 2; ++mt)
; #pragma unroll
;                         for (int i = 0; i < 16; ++i)
;                             if (!(64 * kt + 32 * mt + crow(i, h) < qidx)) sc[mt][i] = 0.f;
;                 }
; #pragma unroll
;                 for (int mt = 0; mt < 2; ++mt)
; #pragma unroll
;                     for (int i = 0; i < 16; ++i) u[mt][i] = 1.f - sc[mt][i];
;                 float p23[2][4], gs[2][4], go[2][4];
; #pragma unroll
;                 for (int mt = 0; mt < 2; ++mt)
; #pragma unroll
;                     for (int qd = 0; qd < 4; ++qd) {
;                         p23[mt][qd] = u[mt][4 * qd + 2] * u[mt][4 * qd + 3];
;                         gs[mt][qd] = (u[mt][4 * qd] * u[mt][4 * qd + 1]) * p23[mt][qd];
;                         go[mt][qd] = xhalf_other(gs[mt][qd], h);
;                     }
;                 float run = R;
; #pragma unroll
;     ...
; #pragma unroll
;     ...
;                         const float ex = h ? run : run * go[mt][qd];
;                         run *= gs[mt][qd] * go[mt][qd];
;                         const float e2 = ex * u[mt][4 * qd + 3], e1 = ex * p23[mt][qd], e0 = e1 * u[mt][4 * qd + 1];
;                         sc[mt][4 * qd + 3] *= ex; sc[mt][4 * qd + 2] *= e2; sc[mt][4 * qd + 1] *= e1; sc[mt][4 * qd] *= e0;
;                     }
;                 R = run;
;             } else {
;                 f32x4 s4[2][4];
; #pragma unroll
;                 for (int mt = 0; mt < 2; ++mt) {
;                     s4[mt][0] = __builtin_shufflevector(sc[mt], sc[mt], 0, 1, 2, 3);
.LBB0_750:
	s_andn2_b64 vcc, exec, s[18:19]
	s_mov_b64 s[18:19], 0
	s_cbranch_vccnz .LBB0_768
	s_add_i32 s48, s14, 64
	s_and_b32 s15, s20, 1
	v_cmp_le_i32_e32 vcc, s48, v133
	s_and_saveexec_b64 s[18:19], vcc
	s_cbranch_execz .LBB0_757
	s_mul_i32 s20, s15, 0x5900
	s_add_i32 s20, s33, s20
	v_lshlrev_b32_e32 v34, 1, v129
	v_add3_u32 v212, s20, v136, v34
	v_lshl_add_u32 v213, v112, 2, s20
	ds_read_b128 v[232:235], v213 offset:22528
	ds_read_b128 v[236:239], v213 offset:22560
	ds_read_b128 v[240:243], v213 offset:22592
	ds_read_b128 v[244:247], v213 offset:22624
	ds_read_b128 v[140:143], v213 offset:22656
	ds_read_b128 v[144:147], v213 offset:22688
	ds_read_b128 v[148:151], v213 offset:22720
	ds_read_b128 v[152:155], v213 offset:22752
	ds_read_b128 v[176:179], v212
	ds_read_b128 v[180:183], v212 offset:4608
	s_add_i32 s20, s14, 0x7f
	ds_read_b128 v[184:187], v212 offset:32
	ds_read_b128 v[188:191], v212 offset:4640
	v_cmp_gt_i32_e32 vcc, s20, v130
	ds_read_b128 v[192:195], v212 offset:64
	ds_read_b128 v[196:199], v212 offset:4672
	s_waitcnt lgkmcnt(4)
	ds_read_b128 v[200:203], v212 offset:96
	ds_read_b128 v[204:207], v212 offset:4704
	s_waitcnt lgkmcnt(6)
	v_mfma_f32_32x32x16_bf16 v[50:65], v[176:179], v[66:69], v[232:247]
	v_mfma_f32_32x32x16_bf16 v[34:49], v[180:183], v[66:69], v[140:155]
	s_waitcnt lgkmcnt(4)
	v_mfma_f32_32x32x16_bf16 v[50:65], v[184:187], v[70:73], v[50:65]
	v_mfma_f32_32x32x16_bf16 v[34:49], v[188:191], v[70:73], v[34:49]
	s_waitcnt lgkmcnt(2)
	v_mfma_f32_32x32x16_bf16 v[50:65], v[192:195], v[74:77], v[50:65]
	v_mfma_f32_32x32x16_bf16 v[34:49], v[196:199], v[74:77], v[34:49]
	s_waitcnt lgkmcnt(0)
	v_mfma_f32_32x32x16_bf16 v[50:65], v[200:203], v[78:81], v[50:65]
	v_mfma_f32_32x32x16_bf16 v[34:49], v[204:207], v[78:81], v[34:49]
	ds_read_b128 v[176:179], v212 offset:13312
	ds_read_b128 v[180:183], v212 offset:17920
	ds_read_b128 v[184:187], v212 offset:13344
	ds_read_b128 v[188:191], v212 offset:17952
	ds_read_b128 v[192:195], v212 offset:13376
	ds_read_b128 v[196:199], v212 offset:17984
	ds_read_b128 v[200:203], v212 offset:13408
	ds_read_b128 v[204:207], v212 offset:18016
	s_nop 3
	s_and_saveexec_b64 s[20:21], vcc
	s_cbranch_execz .Lfox_nomask
	v_sub_u32_e32 v217, v131, v112
	v_subrev_u32_e32 v217, s48, v217
	v_cmp_le_i32_e32 vcc, 0, v217
	s_nop 1
	v_cndmask_b32_e32 v50, v228, v50, vcc
	v_cmp_le_i32_e32 vcc, 1, v217
	s_nop 1
	v_cndmask_b32_e32 v51, v228, v51, vcc
	v_cmp_le_i32_e32 vcc, 2, v217
	s_nop 1
	v_cndmask_b32_e32 v52, v228, v52, vcc
	v_cmp_le_i32_e32 vcc, 3, v217
	s_nop 1
	v_cndmask_b32_e32 v53, v228, v53, vcc
	v_cmp_le_i32_e32 vcc, 8, v217
	s_nop 1
	v_cndmask_b32_e32 v54, v228, v54, vcc
	v_cmp_le_i32_e32 vcc, 9, v217
	s_nop 1
	v_cndmask_b32_e32 v55, v228, v55, vcc
	v_cmp_le_i32_e32 vcc, 10, v217
	s_nop 1
	v_cndmask_b32_e32 v56, v228, v56, vcc
	v_cmp_le_i32_e32 vcc, 11, v217
	s_nop 1
	v_cndmask_b32_e32 v57, v228, v57, vcc
	v_cmp_le_i32_e32 vcc, 16, v217
	s_nop 1
	v_cndmask_b32_e32 v58, v228, v58, vcc
	v_cmp_le_i32_e32 vcc, 17, v217
	s_nop 1
	v_cndmask_b32_e32 v59, v228, v59, vcc
	v_cmp_le_i32_e32 vcc, 18, v217
	s_nop 1
	v_cndmask_b32_e32 v60, v228, v60, vcc
	v_cmp_le_i32_e32 vcc, 19, v217
	s_nop 1
	v_cndmask_b32_e32 v61, v228, v61, vcc
	v_cmp_le_i32_e32 vcc, 24, v217
	s_nop 1
	v_cndmask_b32_e32 v62, v228, v62, vcc
	v_cmp_le_i32_e32 vcc, 25, v217
	s_nop 1
	v_cndmask_b32_e32 v63, v228, v63, vcc
	v_cmp_le_i32_e32 vcc, 26, v217
	s_nop 1
	v_cndmask_b32_e32 v64, v228, v64, vcc
	v_cmp_le_i32_e32 vcc, 27, v217
	s_nop 1
	v_cndmask_b32_e32 v65, v228, v65, vcc
	v_cmp_le_i32_e32 vcc, 32, v217
	s_nop 1
	v_cndmask_b32_e32 v34, v228, v34, vcc
	v_cmp_le_i32_e32 vcc, 33, v217
	s_nop 1
	v_cndmask_b32_e32 v35, v228, v35, vcc
	v_cmp_le_i32_e32 vcc, 34, v217
	s_nop 1
	v_cndmask_b32_e32 v36, v228, v36, vcc
	v_cmp_le_i32_e32 vcc, 35, v217
	s_nop 1
	v_cndmask_b32_e32 v37, v228, v37, vcc
	v_cmp_le_i32_e32 vcc, 40, v217
	s_nop 1
	v_cndmask_b32_e32 v38, v228, v38, vcc
	v_cmp_le_i32_e32 vcc, 41, v217
	s_nop 1
	v_cndmask_b32_e32 v39, v228, v39, vcc
	v_cmp_le_i32_e32 vcc, 42, v217
	s_nop 1
	v_cndmask_b32_e32 v40, v228, v40, vcc
	v_cmp_le_i32_e32 vcc, 43, v217
	s_nop 1
	v_cndmask_b32_e32 v41, v228, v41, vcc
	v_cmp_le_i32_e32 vcc, 48, v217
	s_nop 1
	v_cndmask_b32_e32 v42, v228, v42, vcc
	v_cmp_le_i32_e32 vcc, 49, v217
	s_nop 1
	v_cndmask_b32_e32 v43, v228, v43, vcc
	v_cmp_le_i32_e32 vcc, 50, v217
	s_nop 1
	v_cndmask_b32_e32 v44, v228, v44, vcc
	v_cmp_le_i32_e32 vcc, 51, v217
	s_nop 1
	v_cndmask_b32_e32 v45, v228, v45, vcc
	v_cmp_le_i32_e32 vcc, 56, v217
	s_nop 1
	v_cndmask_b32_e32 v46, v228, v46, vcc
	v_cmp_le_i32_e32 vcc, 57, v217
	s_nop 1
	v_cndmask_b32_e32 v47, v228, v47, vcc
	v_cmp_le_i32_e32 vcc, 58, v217
	s_nop 1
	v_cndmask_b32_e32 v48, v228, v48, vcc
	v_cmp_le_i32_e32 vcc, 59, v217
	s_nop 1
	v_cndmask_b32_e32 v49, v228, v49, vcc
; DI unsigned pk2(float a, float b) { f32x2 v = {a, b}; return __builtin_bit_cast(unsigned, __builtin_convertvector(v, bf2_t)); }
; #define MFMA32(a, b, c) __builtin_amdgcn_mfma_f32_32x32x16_bf16((a), (b), (c), 0, 0, 0)
;     ...
;                 float mx = fmaxf(s4[0][0].x, s4[1][0].x);
; #pragma unroll
;                 for (int qd = 0; qd < 4; ++qd) {
;                     mx = fmaxf(fmaxf(mx, s4[0][qd].y), s4[1][qd].y);
;                     mx = fmaxf(fmaxf(mx, s4[0][qd].z), s4[1][qd].z);
;                     mx = fmaxf(fmaxf(mx, s4[0][qd].w), s4[1][qd].w);
;                     if (qd < 3) mx = fmaxf(fmaxf(mx, s4[0][qd + 1].x), s4[1][qd + 1].x);
;                 }
;                 mx = xhalf_max(mx);
;                 const float mn = fmaxf(m, mx), alpha = fexp2(m - mn);
;                 m = mn;
;                 f32x4 ps4 = {0.f, 0.f, 0.f, 0.f};
;                 const float nmn = -mn;
;                 const f32x4 nm4 = {nmn, nmn, nmn, nmn};
;                 if (__builtin_amdgcn_ballot_w64(alpha != 1.f) != 0) { o0 *= alpha; o1 *= alpha; }
; #pragma unroll
;                 for (int s2 = 0; s2 < 4; ++s2) {
;                     const int mt = s2 >> 1, s = s2 & 1;
;                     f32x4 da = s4[mt][2 * s] + nm4, db = s4[mt][2 * s + 1] + nm4;
;                     da.x = fexp2(da.x); da.y = fexp2(da.y); da.z = fexp2(da.z); da.w = fexp2(da.w);
;                     db.x = fexp2(db.x); db.y = fexp2(db.y); db.z = fexp2(db.z); db.w = fexp2(db.w);
;                     ps4 += da; ps4 += db;
;                     u32x4 pp;
;                     pp.x = pk2(da.x, da.y); pp.y = pk2(da.z, da.w); pp.z = pk2(db.x, db.y); pp.w = pk2(db.z, db.w);
;                     const bf16x8 pfr = __builtin_bit_cast(bf16x8, pp);
;                     const s16x4 a0 = *(const s16x4*)(sV + r * LS + 16 * s2 + 4 * h), a1 = *(const s16x4*)(sV + r * LS + 16 * s2 + 8 + 4 * h);
;                     const s16x4 b0 = *(const s16x4*)(sV + (32 + r) * LS + 16 * s2 + 4 * h), b1 = *(const s16x4*)(sV + (32 + r) * LS + 16 * s2 + 8 + 4 * h);
;                     const bf16x8 v0 = __builtin_shufflevector(a0, a1, 0, 1, 2, 3, 4, 5, 6, 7), v1 = __builtin_shufflevector(b0, b1, 0, 1, 2, 3, 4, 5, 6, 7);
;                     o0 = MFMA32(v0, pfr, o0);
;                     o1 = MFMA32(v1, pfr, o1);
;                 }
;                 lsum = lsum * alpha + ((ps4.x + ps4.y) + (ps4.z + ps4.w));
.Lfox_nomask:
	s_or_b64 exec, exec, s[20:21]
	v_max3_f32 v212, v50, v51, v52
	v_max3_f32 v213, v53, v54, v55
	v_max3_f32 v217, v56, v57, v58
	v_max3_f32 v121, v59, v60, v61
	v_max3_f32 v212, v212, v62, v63
	v_max3_f32 v213, v213, v64, v65
	v_max3_f32 v217, v217, v34, v35
	v_max3_f32 v121, v121, v36, v37
	v_max3_f32 v212, v212, v38, v39
	v_max3_f32 v213, v213, v40, v41
	v_max3_f32 v217, v217, v42, v43
	v_max3_f32 v121, v121, v44, v45
	v_max3_f32 v212, v212, v46, v47
	v_max3_f32 v213, v213, v48, v49
	v_max3_f32 v212, v212, v213, v217
	v_max_f32_e32 v212, v212, v121
	v_mov_b32_e32 v213, v212
	s_nop 1
	v_permlane32_swap_b32_e32 v212, v213
	v_max3_f32 v212, v139, v212, v213
	v_sub_f32_e32 v216, v139, v212
	v_exp_f32_e32 v216, v216
	v_mov_b32_e32 v139, v212
	v_cmp_neq_f32_e32 vcc, 1.0, v216
	s_cbranch_vccz .Lfox_norescale
	v_pk_mul_f32 v[32:33], v[32:33], v[216:217] op_sel_hi:[1,0]
	v_pk_mul_f32 v[30:31], v[30:31], v[216:217] op_sel_hi:[1,0]
	v_pk_mul_f32 v[28:29], v[28:29], v[216:217] op_sel_hi:[1,0]
	v_pk_mul_f32 v[26:27], v[26:27], v[216:217] op_sel_hi:[1,0]
	v_pk_mul_f32 v[24:25], v[24:25], v[216:217] op_sel_hi:[1,0]
	v_pk_mul_f32 v[22:23], v[22:23], v[216:217] op_sel_hi:[1,0]
	v_pk_mul_f32 v[20:21], v[20:21], v[216:217] op_sel_hi:[1,0]
	v_pk_mul_f32 v[18:19], v[18:19], v[216:217] op_sel_hi:[1,0]
	v_pk_mul_f32 v[16:17], v[16:17], v[216:217] op_sel_hi:[1,0]
	v_pk_mul_f32 v[14:15], v[14:15], v[216:217] op_sel_hi:[1,0]
	v_pk_mul_f32 v[12:13], v[12:13], v[216:217] op_sel_hi:[1,0]
	v_pk_mul_f32 v[10:11], v[10:11], v[216:217] op_sel_hi:[1,0]
	v_pk_mul_f32 v[8:9], v[8:9], v[216:217] op_sel_hi:[1,0]
	v_pk_mul_f32 v[6:7], v[6:7], v[216:217] op_sel_hi:[1,0]
	v_pk_mul_f32 v[4:5], v[4:5], v[216:217] op_sel_hi:[1,0]
	v_pk_mul_f32 v[2:3], v[2:3], v[216:217] op_sel_hi:[1,0]
.Lfox_norescale:
	v_sub_f32_e32 v50, v50, v212
	v_sub_f32_e32 v51, v51, v212
	v_sub_f32_e32 v52, v52, v212
	v_sub_f32_e32 v53, v53, v212
	v_sub_f32_e32 v54, v54, v212
	v_sub_f32_e32 v55, v55, v212
	v_sub_f32_e32 v56, v56, v212
	v_sub_f32_e32 v57, v57, v212
	v_exp_f32_e32 v50, v50
	v_exp_f32_e32 v51, v51
	v_exp_f32_e32 v52, v52
	v_exp_f32_e32 v53, v53
	v_exp_f32_e32 v54, v54
	v_exp_f32_e32 v55, v55
	v_exp_f32_e32 v56, v56
	v_exp_f32_e32 v57, v57
	v_cvt_pk_bf16_f32 v232, v50, v51
	v_cvt_pk_bf16_f32 v233, v52, v53
	v_cvt_pk_bf16_f32 v234, v54, v55
	v_cvt_pk_bf16_f32 v235, v56, v57
	s_waitcnt lgkmcnt(0)
	v_sub_f32_e32 v58, v58, v212
	v_sub_f32_e32 v59, v59, v212
	v_sub_f32_e32 v60, v60, v212
	v_sub_f32_e32 v61, v61, v212
	v_sub_f32_e32 v62, v62, v212
	v_sub_f32_e32 v63, v63, v212
	v_sub_f32_e32 v64, v64, v212
	v_sub_f32_e32 v65, v65, v212
	v_mfma_f32_32x32x16_bf16 v[18:33], v[176:179], v[232:235], v[18:33]
	v_exp_f32_e32 v58, v58
	v_exp_f32_e32 v59, v59
	v_exp_f32_e32 v60, v60
	v_exp_f32_e32 v61, v61
	v_mfma_f32_32x32x16_bf16 v[2:17], v[180:183], v[232:235], v[2:17]
	v_exp_f32_e32 v62, v62
	v_exp_f32_e32 v63, v63
	v_exp_f32_e32 v64, v64
	v_exp_f32_e32 v65, v65
	v_add_f32_e32 v116, v50, v51
	v_add_f32_e32 v117, v52, v53
	v_add_f32_e32 v118, v54, v55
	v_add_f32_e32 v119, v56, v57
	v_add_f32_e32 v116, v116, v117
	v_add_f32_e32 v118, v118, v119
	v_add_f32_e32 v120, v116, v118
	v_cvt_pk_bf16_f32 v236, v58, v59
	v_cvt_pk_bf16_f32 v237, v60, v61
	v_cvt_pk_bf16_f32 v238, v62, v63
	v_cvt_pk_bf16_f32 v239, v64, v65
	v_sub_f32_e32 v34, v34, v212
	v_sub_f32_e32 v35, v35, v212
	v_sub_f32_e32 v36, v36, v212
	v_sub_f32_e32 v37, v37, v212
	v_sub_f32_e32 v38, v38, v212
	v_sub_f32_e32 v39, v39, v212
	v_sub_f32_e32 v40, v40, v212
	v_sub_f32_e32 v41, v41, v212
	v_mfma_f32_32x32x16_bf16 v[18:33], v[184:187], v[236:239], v[18:33]
	v_exp_f32_e32 v34, v34
	v_exp_f32_e32 v35, v35
	v_exp_f32_e32 v36, v36
	v_exp_f32_e32 v37, v37
	v_mfma_f32_32x32x16_bf16 v[2:17], v[188:191], v[236:239], v[2:17]
	v_exp_f32_e32 v38, v38
	v_exp_f32_e32 v39, v39
	v_exp_f32_e32 v40, v40
	v_exp_f32_e32 v41, v41
	v_add_f32_e32 v116, v58, v59
	v_add_f32_e32 v117, v60, v61
	v_add_f32_e32 v118, v62, v63
	v_add_f32_e32 v119, v64, v65
	v_add_f32_e32 v116, v116, v117
	v_add_f32_e32 v118, v118, v119
	v_add_f32_e32 v116, v116, v118
	v_add_f32_e32 v120, v120, v116
	v_cvt_pk_bf16_f32 v240, v34, v35
	v_cvt_pk_bf16_f32 v241, v36, v37
	v_cvt_pk_bf16_f32 v242, v38, v39
	v_cvt_pk_bf16_f32 v243, v40, v41
	v_sub_f32_e32 v42, v42, v212
	v_sub_f32_e32 v43, v43, v212
	v_sub_f32_e32 v44, v44, v212
	v_sub_f32_e32 v45, v45, v212
	v_sub_f32_e32 v46, v46, v212
	v_sub_f32_e32 v47, v47, v212
	v_sub_f32_e32 v48, v48, v212
	v_sub_f32_e32 v49, v49, v212
	v_mfma_f32_32x32x16_bf16 v[18:33], v[192:195], v[240:243], v[18:33]
	v_exp_f32_e32 v42, v42
	v_exp_f32_e32 v43, v43
	v_exp_f32_e32 v44, v44
	v_exp_f32_e32 v45, v45
	v_mfma_f32_32x32x16_bf16 v[2:17], v[196:199], v[240:243], v[2:17]
	v_exp_f32_e32 v46, v46
	v_exp_f32_e32 v47, v47
	v_exp_f32_e32 v48, v48
	v_exp_f32_e32 v49, v49
	v_add_f32_e32 v116, v34, v35
	v_add_f32_e32 v117, v36, v37
	v_add_f32_e32 v118, v38, v39
	v_add_f32_e32 v119, v40, v41
	v_add_f32_e32 v116, v116, v117
	v_add_f32_e32 v118, v118, v119
	v_add_f32_e32 v116, v116, v118
	v_add_f32_e32 v120, v120, v116
	v_cvt_pk_bf16_f32 v244, v42, v43
	v_cvt_pk_bf16_f32 v245, v44, v45
	v_cvt_pk_bf16_f32 v246, v46, v47
	v_cvt_pk_bf16_f32 v247, v48, v49
	v_add_f32_e32 v116, v42, v43
	v_add_f32_e32 v117, v44, v45
	v_add_f32_e32 v118, v46, v47
	v_add_f32_e32 v119, v48, v49
	v_mfma_f32_32x32x16_bf16 v[18:33], v[200:203], v[244:247], v[18:33]
	v_mfma_f32_32x32x16_bf16 v[2:17], v[204:207], v[244:247], v[2:17]
	v_add_f32_e32 v116, v116, v117
	v_add_f32_e32 v118, v118, v119
	v_add_f32_e32 v116, v116, v118
	v_add_f32_e32 v120, v120, v116
	v_fma_f32 v111, v111, v216, v120
